# grid barrier: the last-arriving XCD leader bumps every XCD's release-generation word itself (broadcast release) so the other leaders no longer relay the release to their workgroups
# baseline (speedup 1.0000x reference)
; __device__ __forceinline__ unsigned xb_ld(unsigned* p)              { return __hip_atomic_load(p, __ATOMIC_RELAXED, __HIP_MEMORY_SCOPE_AGENT); }
; __device__ __forceinline__ unsigned xb_add(unsigned* p, unsigned v) { return __hip_atomic_fetch_add(p, v, __ATOMIC_RELAXED, __HIP_MEMORY_SCOPE_AGENT); }
; #define XB_SPIN(cond, bar) do { unsigned _sp = 0; while (cond) { __builtin_amdgcn_s_sleep(1); \
;     if ((++_sp & 255u) == 0u) { if (xb_ld(&(bar)[XB_TMO])) break; if (_sp > XB_SPIN_CAP) { atomicAdd(&(bar)[XB_TMO], 1u); break; } } } } while (0)
; __device__ __forceinline__ void xcd_barrier(const XcdBarrier& b) {
;     ...
;             const unsigned og = xb_add(&bar[XB_TOP], 1u);
;             const unsigned tg = og / nx;
;             if (og + 1u == (tg + 1u) * nx) xb_add(&bar[XB_TOPGEN], 1u);
;             else XB_SPIN(xb_ld(&bar[XB_TOPGEN]) == tg, bar);
;             __builtin_amdgcn_fence(__ATOMIC_ACQUIRE, "agent");
;             xb_add(&bar[XB_XGEN(b.x)], 1u);
;             asm volatile("s_waitcnt vmcnt(0)" ::: "memory");
.LBB0_524:
	s_or_b64 exec, exec, s[26:27]
	s_and_saveexec_b64 s[26:27], s[40:41]
	s_cbranch_execz .LBB0_526
	v_readlane_b32 s4, v254, 38
	v_readlane_b32 s5, v254, 39
	s_nop 4
	global_atomic_add v0, v209, s[4:5] offset:-4096
	global_atomic_add v0, v209, s[4:5] offset:-3840
	global_atomic_add v0, v209, s[4:5] offset:-3584
	global_atomic_add v0, v209, s[4:5] offset:-3328
	global_atomic_add v0, v209, s[4:5] offset:-3072
	global_atomic_add v0, v209, s[4:5] offset:-2816
	global_atomic_add v0, v209, s[4:5] offset:-2560
	global_atomic_add v0, v209, s[4:5] offset:-2304
	global_atomic_add v[2:3], v209, off
	global_atomic_add v0, v209, s[4:5] offset:-2048
	global_atomic_add v0, v209, s[4:5] offset:-1792
	global_atomic_add v0, v209, s[4:5] offset:-1536
	global_atomic_add v0, v209, s[4:5] offset:-1280
	global_atomic_add v0, v209, s[4:5] offset:-1024
	global_atomic_add v0, v209, s[4:5] offset:-768
	global_atomic_add v0, v209, s[4:5] offset:-512
	global_atomic_add v0, v209, s[4:5] offset:-256
.LBB0_526:
	s_or_b64 exec, exec, s[26:27]
	s_mov_b64 s[26:27], exec
	v_mbcnt_lo_u32_b32 v1, s26, 0
	v_mbcnt_hi_u32_b32 v1, s27, v1
	v_cmp_eq_u32_e32 vcc, 0, v1
	s_and_saveexec_b64 s[40:41], vcc
	s_cbranch_execz .LBB0_528
	s_bcnt1_i32_b64 s2, s[26:27]
	v_readlane_b32 s4, v254, 36
	v_mov_b32_e32 v1, s2
	v_readlane_b32 s5, v254, 37
	s_nop 4
.LBB0_528:
	s_or_b64 exec, exec, s[40:41]
	buffer_inv sc1
	s_waitcnt vmcnt(0)
